# P0 rmsnorm row loop hand-written: the next row's loads are issued before the current row is reduced and stored
# speedup vs baseline: 1.0000x; 1.0000x over previous
; __device__ __forceinline__ u32x2 pack4(f32x4 a) { u32x2 w; w.x = cvt_pk_bf16(a[0], a[1]); w.y = cvt_pk_bf16(a[2], a[3]); return w; }
; __device__ __forceinline__ void p0_prologue(const Params& p, LAS unsigned char* lds, const int wave_s) {
;     ...
;     bf16_t* H = (bf16_t*)(ws + WS_H);
;     f32x4 g1[4];
; #pragma unroll
;     for (int i = 0; i < 4; ++i) g1[i] = *(const f32x4*)(p.in[I_N1G] + lane * 4 + 256 * i);
;     for (int row = blockIdx.x * 8 + wid; row < MTOK; row += G * 8) {
;         const float* xr = (row < NPROMPT ? p.in[I_XP] + (size_t)row * DM : p.in[I_XS] + (size_t)(row - NPROMPT) * DM) + lane * 4;
;         f32x4 v[4]; float ss = 0.f;
; #pragma unroll
;         for (int i = 0; i < 4; ++i) { v[i] = *(const f32x4*)(xr + 256 * i); ss += (v[i][0] * v[i][0] + v[i][1] * v[i][1]) + (v[i][2] * v[i][2] + v[i][3] * v[i][3]); }
; #pragma unroll
;         for (int o = 1; o < 64; o <<= 1) ss += __shfl_xor(ss, o);
;         const float rstd = rsqrtf(ss * (1.0f / 1024.0f) + EPSV);
;         bf16_t* hr = H + (size_t)row * DM + lane * 4;
; #pragma unroll
;         for (int i = 0; i < 4; ++i) *(u32x2*)(hr + 256 * i) = pack4(v[i] * rstd * g1[i]);
;     }
.LBB0_198:
	s_or_b64 exec, exec, s[0:1]
	s_add_u32 s20, s80, 0x21a00000
	s_addc_u32 s21, s81, 0
	s_lshl_b32 s23, s93, 3
	v_add_u32_e32 v18, s23, v53
	s_mov_b32 s0, 0x20000
	v_cmp_gt_i32_e32 vcc, s0, v18
	v_mbcnt_lo_u32_b32 v254, -1, 0
	s_and_saveexec_b64 s[2:3], vcc
	s_cbranch_execz .LBB0_203
	v_lshlrev_b32_e32 v1, 4, v42
	s_waitcnt lgkmcnt(0)
	global_load_dwordx4 v[2:5], v1, s[40:41]
	global_load_dwordx4 v[6:9], v1, s[40:41] offset:1024
	global_load_dwordx4 v[10:13], v1, s[40:41] offset:2048
	global_load_dwordx4 v[14:17], v1, s[40:41] offset:3072
	v_mbcnt_hi_u32_b32 v19, -1, v254
	v_and_b32_e32 v1, 64, v19
	v_mov_b32_e32 v21, 0
	v_add_u32_e32 v24, 64, v1
	v_lshlrev_b32_e32 v20, 3, v42
	v_xor_b32_e32 v1, 1, v19
	v_lshl_add_u64 v[22:23], s[20:21], 0, v[20:21]
	v_cmp_lt_i32_e32 vcc, v1, v24
	v_xor_b32_e32 v20, 2, v19
	s_lshl_b32 s4, s82, 3
	v_cndmask_b32_e32 v1, v19, v1, vcc
	v_cmp_lt_i32_e32 vcc, v20, v24
	v_lshlrev_b32_e32 v26, 2, v42
	s_ashr_i32 s5, s4, 31
	v_cndmask_b32_e32 v20, v19, v20, vcc
	v_lshlrev_b32_e32 v32, 2, v20
	v_xor_b32_e32 v20, 4, v19
	v_cmp_lt_i32_e32 vcc, v20, v24
	v_lshlrev_b32_e32 v1, 2, v1
	s_lshl_b64 s[8:9], s[4:5], 12
	v_cndmask_b32_e32 v20, v19, v20, vcc
	v_lshlrev_b32_e32 v33, 2, v20
	v_xor_b32_e32 v20, 8, v19
	v_cmp_lt_i32_e32 vcc, v20, v24
	s_mov_b64 s[10:11], 0
	s_mov_b32 s12, 0xffff
	v_cndmask_b32_e32 v20, v19, v20, vcc
	v_lshlrev_b32_e32 v34, 2, v20
	v_xor_b32_e32 v20, 16, v19
	v_cmp_lt_i32_e32 vcc, v20, v24
	v_lshlrev_b32_e32 v26, 2, v26
	v_mov_b32_e32 v27, v21
	v_cndmask_b32_e32 v20, v19, v20, vcc
	v_lshlrev_b32_e32 v35, 2, v20
	v_xor_b32_e32 v20, 32, v19
	v_cmp_lt_i32_e32 vcc, v20, v24
	v_mov_b32_e32 v37, 0x358637bd
	s_mov_b32 s13, 0x800000
	v_cndmask_b32_e32 v19, v19, v20, vcc
	v_lshlrev_b32_e32 v36, 2, v19
	v_ashrrev_i32_e32 v19, 31, v18
	v_lshlrev_b64 v[24:25], 12, v[18:19]
	v_lshl_add_u64 v[24:25], s[36:37], 0, v[24:25]
	s_mov_b32 s14, 0x1ffff
	v_readfirstlane_b32 s24, v18
	v_lshlrev_b32_e32 v72, 3, v42
	s_nop 3
	s_lshl_b32 s25, s24, 12
	s_add_u32 s26, s36, s25
	s_addc_u32 s27, s37, 0
	s_add_u32 s34, s38, s25
	s_addc_u32 s35, s39, 0
	s_lshl_b32 s25, s24, 11
	s_add_u32 s28, s20, s25
	s_addc_u32 s29, s21, 0
	s_mov_b32 s30, 0
	global_load_dwordx4 v[38:41], v26, s[26:27]
	global_load_dwordx4 v[44:47], v26, s[26:27] offset:1024
	global_load_dwordx4 v[48:51], v26, s[26:27] offset:2048
	global_load_dwordx4 v[52:55], v26, s[26:27] offset:3072
	s_add_u32 s26, s26, 0x800000
	s_addc_u32 s27, s27, 0
	s_add_i32 s30, s30, 1
	s_cmp_eq_u32 s30, 32
	s_cselect_b32 s26, s34, s26
	s_cselect_b32 s27, s35, s27
	global_load_dwordx4 v[56:59], v26, s[26:27]
	global_load_dwordx4 v[60:63], v26, s[26:27] offset:1024
	global_load_dwordx4 v[64:67], v26, s[26:27] offset:2048
	global_load_dwordx4 v[68:71], v26, s[26:27] offset:3072
	s_waitcnt vmcnt(4)
	v_mul_f32_e32 v74, v38, v38
	v_fmac_f32_e32 v74, v39, v39
	v_mul_f32_e32 v75, v40, v40
	v_fmac_f32_e32 v75, v41, v41
	v_add_f32_e32 v74, v74, v75
	v_mov_b32_e32 v73, v74
	v_mul_f32_e32 v74, v44, v44
	v_fmac_f32_e32 v74, v45, v45
	v_mul_f32_e32 v75, v46, v46
	v_fmac_f32_e32 v75, v47, v47
	v_add_f32_e32 v74, v74, v75
	v_add_f32_e32 v73, v73, v74
	v_mul_f32_e32 v74, v48, v48
	v_fmac_f32_e32 v74, v49, v49
	v_mul_f32_e32 v75, v50, v50
	v_fmac_f32_e32 v75, v51, v51
	v_add_f32_e32 v74, v74, v75
	v_add_f32_e32 v73, v73, v74
	v_mul_f32_e32 v74, v52, v52
	v_fmac_f32_e32 v74, v53, v53
	v_mul_f32_e32 v75, v54, v54
	v_fmac_f32_e32 v75, v55, v55
	v_add_f32_e32 v74, v74, v75
	v_add_f32_e32 v73, v73, v74
	ds_bpermute_b32 v74, v1, v73
	s_waitcnt lgkmcnt(0)
	v_add_f32_e32 v73, v73, v74
	ds_bpermute_b32 v74, v32, v73
	s_waitcnt lgkmcnt(0)
	v_add_f32_e32 v73, v73, v74
	ds_bpermute_b32 v74, v33, v73
	s_waitcnt lgkmcnt(0)
	v_add_f32_e32 v73, v73, v74
	ds_bpermute_b32 v74, v34, v73
	s_waitcnt lgkmcnt(0)
	v_add_f32_e32 v73, v73, v74
	ds_bpermute_b32 v74, v35, v73
	s_waitcnt lgkmcnt(0)
	v_add_f32_e32 v73, v73, v74
	ds_bpermute_b32 v74, v36, v73
	s_waitcnt lgkmcnt(0)
	v_add_f32_e32 v73, v73, v74
	v_fmamk_f32 v73, v73, 0x3a800000, v37
	v_mul_f32_e32 v74, 0x4b800000, v73
	v_cmp_gt_f32_e32 vcc, s13, v73
	s_nop 1
	v_cndmask_b32_e32 v73, v73, v74, vcc
	v_rsq_f32_e32 v73, v73
	s_nop 0
	v_mul_f32_e32 v74, 0x45800000, v73
	v_cndmask_b32_e32 v77, v73, v74, vcc
	v_mul_f32_e32 v38, v38, v77
	v_mul_f32_e32 v38, v2, v38
	v_mul_f32_e32 v39, v39, v77
	v_mul_f32_e32 v39, v3, v39
	v_mul_f32_e32 v40, v40, v77
	v_mul_f32_e32 v40, v4, v40
	v_mul_f32_e32 v41, v41, v77
	v_mul_f32_e32 v41, v5, v41
	v_cvt_pk_bf16_f32 v38, v38, v39
	v_cvt_pk_bf16_f32 v39, v40, v41
	global_store_dwordx2 v72, v[38:39], s[28:29]
	v_mul_f32_e32 v44, v44, v77
	v_mul_f32_e32 v44, v6, v44
	v_mul_f32_e32 v45, v45, v77
	v_mul_f32_e32 v45, v7, v45
	v_mul_f32_e32 v46, v46, v77
	v_mul_f32_e32 v46, v8, v46
	v_mul_f32_e32 v47, v47, v77
	v_mul_f32_e32 v47, v9, v47
	v_cvt_pk_bf16_f32 v44, v44, v45
	v_cvt_pk_bf16_f32 v45, v46, v47
	global_store_dwordx2 v72, v[44:45], s[28:29] offset:512
	v_mul_f32_e32 v48, v48, v77
	v_mul_f32_e32 v48, v10, v48
	v_mul_f32_e32 v49, v49, v77
	v_mul_f32_e32 v49, v11, v49
	v_mul_f32_e32 v50, v50, v77
	v_mul_f32_e32 v50, v12, v50
	v_mul_f32_e32 v51, v51, v77
	v_mul_f32_e32 v51, v13, v51
	v_cvt_pk_bf16_f32 v48, v48, v49
	v_cvt_pk_bf16_f32 v49, v50, v51
	global_store_dwordx2 v72, v[48:49], s[28:29] offset:1024
	v_mul_f32_e32 v52, v52, v77
	v_mul_f32_e32 v52, v14, v52
	v_mul_f32_e32 v53, v53, v77
	v_mul_f32_e32 v53, v15, v53
	v_mul_f32_e32 v54, v54, v77
	v_mul_f32_e32 v54, v16, v54
	v_mul_f32_e32 v55, v55, v77
	v_mul_f32_e32 v55, v17, v55
	v_cvt_pk_bf16_f32 v52, v52, v53
	v_cvt_pk_bf16_f32 v53, v54, v55
	global_store_dwordx2 v72, v[52:53], s[28:29] offset:1536
	s_add_u32 s28, s28, 0x400000
	s_addc_u32 s29, s29, 0
	s_add_u32 s26, s26, 0x800000
	s_addc_u32 s27, s27, 0
	s_add_i32 s30, s30, 1
	s_cmp_eq_u32 s30, 32
	s_cselect_b32 s26, s34, s26
	s_cselect_b32 s27, s35, s27
	global_load_dwordx4 v[38:41], v26, s[26:27]
	global_load_dwordx4 v[44:47], v26, s[26:27] offset:1024
	global_load_dwordx4 v[48:51], v26, s[26:27] offset:2048
	global_load_dwordx4 v[52:55], v26, s[26:27] offset:3072
	s_waitcnt vmcnt(8)
; __device__ __forceinline__ u32x2 pack4(f32x4 a) { u32x2 w; w.x = cvt_pk_bf16(a[0], a[1]); w.y = cvt_pk_bf16(a[2], a[3]); return w; }
; __device__ __forceinline__ void p0_prologue(const Params& p, LAS unsigned char* lds, const int wave_s) {
;     ...
;     for (int row = blockIdx.x * 8 + wid; row < MTOK; row += G * 8) {
;         const float* xr = (row < NPROMPT ? p.in[I_XP] + (size_t)row * DM : p.in[I_XS] + (size_t)(row - NPROMPT) * DM) + lane * 4;
;         f32x4 v[4]; float ss = 0.f;
; #pragma unroll
;         for (int i = 0; i < 4; ++i) { v[i] = *(const f32x4*)(xr + 256 * i); ss += (v[i][0] * v[i][0] + v[i][1] * v[i][1]) + (v[i][2] * v[i][2] + v[i][3] * v[i][3]); }
; #pragma unroll
;         for (int o = 1; o < 64; o <<= 1) ss += __shfl_xor(ss, o);
;         const float rstd = rsqrtf(ss * (1.0f / 1024.0f) + EPSV);
;         bf16_t* hr = H + (size_t)row * DM + lane * 4;
; #pragma unroll
;         for (int i = 0; i < 4; ++i) *(u32x2*)(hr + 256 * i) = pack4(v[i] * rstd * g1[i]);
;     }
	v_mul_f32_e32 v74, v56, v56
	v_fmac_f32_e32 v74, v57, v57
	v_mul_f32_e32 v75, v58, v58
	v_fmac_f32_e32 v75, v59, v59
	v_add_f32_e32 v74, v74, v75
	v_mov_b32_e32 v73, v74
	v_mul_f32_e32 v74, v60, v60
	v_fmac_f32_e32 v74, v61, v61
	v_mul_f32_e32 v75, v62, v62
	v_fmac_f32_e32 v75, v63, v63
	v_add_f32_e32 v74, v74, v75
	v_add_f32_e32 v73, v73, v74
	v_mul_f32_e32 v74, v64, v64
	v_fmac_f32_e32 v74, v65, v65
	v_mul_f32_e32 v75, v66, v66
	v_fmac_f32_e32 v75, v67, v67
	v_add_f32_e32 v74, v74, v75
	v_add_f32_e32 v73, v73, v74
	v_mul_f32_e32 v74, v68, v68
	v_fmac_f32_e32 v74, v69, v69
	v_mul_f32_e32 v75, v70, v70
	v_fmac_f32_e32 v75, v71, v71
	v_add_f32_e32 v74, v74, v75
	v_add_f32_e32 v73, v73, v74
	ds_bpermute_b32 v74, v1, v73
	s_waitcnt lgkmcnt(0)
	v_add_f32_e32 v73, v73, v74
	ds_bpermute_b32 v74, v32, v73
	s_waitcnt lgkmcnt(0)
	v_add_f32_e32 v73, v73, v74
	ds_bpermute_b32 v74, v33, v73
	s_waitcnt lgkmcnt(0)
	v_add_f32_e32 v73, v73, v74
	ds_bpermute_b32 v74, v34, v73
	s_waitcnt lgkmcnt(0)
	v_add_f32_e32 v73, v73, v74
	ds_bpermute_b32 v74, v35, v73
	s_waitcnt lgkmcnt(0)
	v_add_f32_e32 v73, v73, v74
	ds_bpermute_b32 v74, v36, v73
	s_waitcnt lgkmcnt(0)
	v_add_f32_e32 v73, v73, v74
	v_fmamk_f32 v73, v73, 0x3a800000, v37
	v_mul_f32_e32 v74, 0x4b800000, v73
	v_cmp_gt_f32_e32 vcc, s13, v73
	s_nop 1
	v_cndmask_b32_e32 v73, v73, v74, vcc
	v_rsq_f32_e32 v73, v73
	s_nop 0
	v_mul_f32_e32 v74, 0x45800000, v73
	v_cndmask_b32_e32 v77, v73, v74, vcc
	v_mul_f32_e32 v56, v56, v77
	v_mul_f32_e32 v56, v2, v56
	v_mul_f32_e32 v57, v57, v77
	v_mul_f32_e32 v57, v3, v57
	v_mul_f32_e32 v58, v58, v77
	v_mul_f32_e32 v58, v4, v58
	v_mul_f32_e32 v59, v59, v77
	v_mul_f32_e32 v59, v5, v59
	v_cvt_pk_bf16_f32 v56, v56, v57
	v_cvt_pk_bf16_f32 v57, v58, v59
	global_store_dwordx2 v72, v[56:57], s[28:29]
	v_mul_f32_e32 v60, v60, v77
	v_mul_f32_e32 v60, v6, v60
	v_mul_f32_e32 v61, v61, v77
	v_mul_f32_e32 v61, v7, v61
	v_mul_f32_e32 v62, v62, v77
	v_mul_f32_e32 v62, v8, v62
	v_mul_f32_e32 v63, v63, v77
	v_mul_f32_e32 v63, v9, v63
	v_cvt_pk_bf16_f32 v60, v60, v61
	v_cvt_pk_bf16_f32 v61, v62, v63
	global_store_dwordx2 v72, v[60:61], s[28:29] offset:512
	v_mul_f32_e32 v64, v64, v77
	v_mul_f32_e32 v64, v10, v64
	v_mul_f32_e32 v65, v65, v77
	v_mul_f32_e32 v65, v11, v65
	v_mul_f32_e32 v66, v66, v77
	v_mul_f32_e32 v66, v12, v66
	v_mul_f32_e32 v67, v67, v77
	v_mul_f32_e32 v67, v13, v67
	v_cvt_pk_bf16_f32 v64, v64, v65
	v_cvt_pk_bf16_f32 v65, v66, v67
	global_store_dwordx2 v72, v[64:65], s[28:29] offset:1024
	v_mul_f32_e32 v68, v68, v77
	v_mul_f32_e32 v68, v14, v68
	v_mul_f32_e32 v69, v69, v77
	v_mul_f32_e32 v69, v15, v69
	v_mul_f32_e32 v70, v70, v77
	v_mul_f32_e32 v70, v16, v70
	v_mul_f32_e32 v71, v71, v77
	v_mul_f32_e32 v71, v17, v71
	v_cvt_pk_bf16_f32 v68, v68, v69
	v_cvt_pk_bf16_f32 v69, v70, v71
	global_store_dwordx2 v72, v[68:69], s[28:29] offset:1536
	s_add_u32 s28, s28, 0x400000
	s_addc_u32 s29, s29, 0
	s_mov_b32 s31, 0
.Lh_loop:
	s_add_u32 s26, s26, 0x800000
	s_addc_u32 s27, s27, 0
	s_add_i32 s30, s30, 1
	s_cmp_eq_u32 s30, 32
	s_cselect_b32 s26, s34, s26
	s_cselect_b32 s27, s35, s27
	global_load_dwordx4 v[56:59], v26, s[26:27]
	global_load_dwordx4 v[60:63], v26, s[26:27] offset:1024
	global_load_dwordx4 v[64:67], v26, s[26:27] offset:2048
	global_load_dwordx4 v[68:71], v26, s[26:27] offset:3072
	s_waitcnt vmcnt(8)
	v_mul_f32_e32 v74, v38, v38
	v_fmac_f32_e32 v74, v39, v39
	v_mul_f32_e32 v75, v40, v40
	v_fmac_f32_e32 v75, v41, v41
	v_add_f32_e32 v74, v74, v75
	v_mov_b32_e32 v73, v74
	v_mul_f32_e32 v74, v44, v44
	v_fmac_f32_e32 v74, v45, v45
	v_mul_f32_e32 v75, v46, v46
	v_fmac_f32_e32 v75, v47, v47
	v_add_f32_e32 v74, v74, v75
	v_add_f32_e32 v73, v73, v74
	v_mul_f32_e32 v74, v48, v48
	v_fmac_f32_e32 v74, v49, v49
	v_mul_f32_e32 v75, v50, v50
	v_fmac_f32_e32 v75, v51, v51
	v_add_f32_e32 v74, v74, v75
	v_add_f32_e32 v73, v73, v74
	v_mul_f32_e32 v74, v52, v52
	v_fmac_f32_e32 v74, v53, v53
	v_mul_f32_e32 v75, v54, v54
	v_fmac_f32_e32 v75, v55, v55
	v_add_f32_e32 v74, v74, v75
	v_add_f32_e32 v73, v73, v74
	ds_bpermute_b32 v74, v1, v73
	s_waitcnt lgkmcnt(0)
	v_add_f32_e32 v73, v73, v74
	ds_bpermute_b32 v74, v32, v73
	s_waitcnt lgkmcnt(0)
	v_add_f32_e32 v73, v73, v74
	ds_bpermute_b32 v74, v33, v73
	s_waitcnt lgkmcnt(0)
	v_add_f32_e32 v73, v73, v74
	ds_bpermute_b32 v74, v34, v73
	s_waitcnt lgkmcnt(0)
	v_add_f32_e32 v73, v73, v74
	ds_bpermute_b32 v74, v35, v73
	s_waitcnt lgkmcnt(0)
	v_add_f32_e32 v73, v73, v74
	ds_bpermute_b32 v74, v36, v73
	s_waitcnt lgkmcnt(0)
	v_add_f32_e32 v73, v73, v74
	v_fmamk_f32 v73, v73, 0x3a800000, v37
	v_mul_f32_e32 v74, 0x4b800000, v73
	v_cmp_gt_f32_e32 vcc, s13, v73
	s_nop 1
	v_cndmask_b32_e32 v73, v73, v74, vcc
	v_rsq_f32_e32 v73, v73
	s_nop 0
	v_mul_f32_e32 v74, 0x45800000, v73
	v_cndmask_b32_e32 v77, v73, v74, vcc
	v_mul_f32_e32 v38, v38, v77
	v_mul_f32_e32 v38, v2, v38
	v_mul_f32_e32 v39, v39, v77
	v_mul_f32_e32 v39, v3, v39
	v_mul_f32_e32 v40, v40, v77
	v_mul_f32_e32 v40, v4, v40
	v_mul_f32_e32 v41, v41, v77
	v_mul_f32_e32 v41, v5, v41
	v_cvt_pk_bf16_f32 v38, v38, v39
	v_cvt_pk_bf16_f32 v39, v40, v41
	global_store_dwordx2 v72, v[38:39], s[28:29]
	v_mul_f32_e32 v44, v44, v77
	v_mul_f32_e32 v44, v6, v44
	v_mul_f32_e32 v45, v45, v77
	v_mul_f32_e32 v45, v7, v45
	v_mul_f32_e32 v46, v46, v77
	v_mul_f32_e32 v46, v8, v46
	v_mul_f32_e32 v47, v47, v77
	v_mul_f32_e32 v47, v9, v47
	v_cvt_pk_bf16_f32 v44, v44, v45
	v_cvt_pk_bf16_f32 v45, v46, v47
	global_store_dwordx2 v72, v[44:45], s[28:29] offset:512
	v_mul_f32_e32 v48, v48, v77
	v_mul_f32_e32 v48, v10, v48
	v_mul_f32_e32 v49, v49, v77
	v_mul_f32_e32 v49, v11, v49
	v_mul_f32_e32 v50, v50, v77
	v_mul_f32_e32 v50, v12, v50
	v_mul_f32_e32 v51, v51, v77
	v_mul_f32_e32 v51, v13, v51
	v_cvt_pk_bf16_f32 v48, v48, v49
	v_cvt_pk_bf16_f32 v49, v50, v51
	global_store_dwordx2 v72, v[48:49], s[28:29] offset:1024
	v_mul_f32_e32 v52, v52, v77
	v_mul_f32_e32 v52, v14, v52
	v_mul_f32_e32 v53, v53, v77
	v_mul_f32_e32 v53, v15, v53
	v_mul_f32_e32 v54, v54, v77
	v_mul_f32_e32 v54, v16, v54
	v_mul_f32_e32 v55, v55, v77
	v_mul_f32_e32 v55, v17, v55
	v_cvt_pk_bf16_f32 v52, v52, v53
	v_cvt_pk_bf16_f32 v53, v54, v55
	global_store_dwordx2 v72, v[52:53], s[28:29] offset:1536
	s_add_u32 s28, s28, 0x400000
	s_addc_u32 s29, s29, 0
	s_add_u32 s26, s26, 0x800000
	s_addc_u32 s27, s27, 0
	s_add_i32 s30, s30, 1
	s_cmp_eq_u32 s30, 32
	s_cselect_b32 s26, s34, s26
	s_cselect_b32 s27, s35, s27
	global_load_dwordx4 v[38:41], v26, s[26:27]
	global_load_dwordx4 v[44:47], v26, s[26:27] offset:1024
	global_load_dwordx4 v[48:51], v26, s[26:27] offset:2048
	global_load_dwordx4 v[52:55], v26, s[26:27] offset:3072
	s_waitcnt vmcnt(8)
; __device__ __forceinline__ u32x2 pack4(f32x4 a) { u32x2 w; w.x = cvt_pk_bf16(a[0], a[1]); w.y = cvt_pk_bf16(a[2], a[3]); return w; }
; __device__ __forceinline__ void p0_prologue(const Params& p, LAS unsigned char* lds, const int wave_s) {
;     ...
;     for (int row = blockIdx.x * 8 + wid; row < MTOK; row += G * 8) {
;         const float* xr = (row < NPROMPT ? p.in[I_XP] + (size_t)row * DM : p.in[I_XS] + (size_t)(row - NPROMPT) * DM) + lane * 4;
;         f32x4 v[4]; float ss = 0.f;
; #pragma unroll
;         for (int i = 0; i < 4; ++i) { v[i] = *(const f32x4*)(xr + 256 * i); ss += (v[i][0] * v[i][0] + v[i][1] * v[i][1]) + (v[i][2] * v[i][2] + v[i][3] * v[i][3]); }
; #pragma unroll
;         for (int o = 1; o < 64; o <<= 1) ss += __shfl_xor(ss, o);
;         const float rstd = rsqrtf(ss * (1.0f / 1024.0f) + EPSV);
;         bf16_t* hr = H + (size_t)row * DM + lane * 4;
; #pragma unroll
;         for (int i = 0; i < 4; ++i) *(u32x2*)(hr + 256 * i) = pack4(v[i] * rstd * g1[i]);
;     }
	v_mul_f32_e32 v74, v56, v56
	v_fmac_f32_e32 v74, v57, v57
	v_mul_f32_e32 v75, v58, v58
	v_fmac_f32_e32 v75, v59, v59
	v_add_f32_e32 v74, v74, v75
	v_mov_b32_e32 v73, v74
	v_mul_f32_e32 v74, v60, v60
	v_fmac_f32_e32 v74, v61, v61
	v_mul_f32_e32 v75, v62, v62
	v_fmac_f32_e32 v75, v63, v63
	v_add_f32_e32 v74, v74, v75
	v_add_f32_e32 v73, v73, v74
	v_mul_f32_e32 v74, v64, v64
	v_fmac_f32_e32 v74, v65, v65
	v_mul_f32_e32 v75, v66, v66
	v_fmac_f32_e32 v75, v67, v67
	v_add_f32_e32 v74, v74, v75
	v_add_f32_e32 v73, v73, v74
	v_mul_f32_e32 v74, v68, v68
	v_fmac_f32_e32 v74, v69, v69
	v_mul_f32_e32 v75, v70, v70
	v_fmac_f32_e32 v75, v71, v71
	v_add_f32_e32 v74, v74, v75
	v_add_f32_e32 v73, v73, v74
	ds_bpermute_b32 v74, v1, v73
	s_waitcnt lgkmcnt(0)
	v_add_f32_e32 v73, v73, v74
	ds_bpermute_b32 v74, v32, v73
	s_waitcnt lgkmcnt(0)
	v_add_f32_e32 v73, v73, v74
	ds_bpermute_b32 v74, v33, v73
	s_waitcnt lgkmcnt(0)
	v_add_f32_e32 v73, v73, v74
	ds_bpermute_b32 v74, v34, v73
	s_waitcnt lgkmcnt(0)
	v_add_f32_e32 v73, v73, v74
	ds_bpermute_b32 v74, v35, v73
	s_waitcnt lgkmcnt(0)
	v_add_f32_e32 v73, v73, v74
	ds_bpermute_b32 v74, v36, v73
	s_waitcnt lgkmcnt(0)
	v_add_f32_e32 v73, v73, v74
	v_fmamk_f32 v73, v73, 0x3a800000, v37
	v_mul_f32_e32 v74, 0x4b800000, v73
	v_cmp_gt_f32_e32 vcc, s13, v73
	s_nop 1
	v_cndmask_b32_e32 v73, v73, v74, vcc
	v_rsq_f32_e32 v73, v73
	s_nop 0
	v_mul_f32_e32 v74, 0x45800000, v73
	v_cndmask_b32_e32 v77, v73, v74, vcc
	v_mul_f32_e32 v56, v56, v77
	v_mul_f32_e32 v56, v2, v56
	v_mul_f32_e32 v57, v57, v77
	v_mul_f32_e32 v57, v3, v57
	v_mul_f32_e32 v58, v58, v77
	v_mul_f32_e32 v58, v4, v58
	v_mul_f32_e32 v59, v59, v77
	v_mul_f32_e32 v59, v5, v59
	v_cvt_pk_bf16_f32 v56, v56, v57
	v_cvt_pk_bf16_f32 v57, v58, v59
	global_store_dwordx2 v72, v[56:57], s[28:29]
	v_mul_f32_e32 v60, v60, v77
	v_mul_f32_e32 v60, v6, v60
	v_mul_f32_e32 v61, v61, v77
	v_mul_f32_e32 v61, v7, v61
	v_mul_f32_e32 v62, v62, v77
	v_mul_f32_e32 v62, v8, v62
	v_mul_f32_e32 v63, v63, v77
	v_mul_f32_e32 v63, v9, v63
	v_cvt_pk_bf16_f32 v60, v60, v61
	v_cvt_pk_bf16_f32 v61, v62, v63
	global_store_dwordx2 v72, v[60:61], s[28:29] offset:512
	v_mul_f32_e32 v64, v64, v77
	v_mul_f32_e32 v64, v10, v64
	v_mul_f32_e32 v65, v65, v77
	v_mul_f32_e32 v65, v11, v65
	v_mul_f32_e32 v66, v66, v77
	v_mul_f32_e32 v66, v12, v66
	v_mul_f32_e32 v67, v67, v77
	v_mul_f32_e32 v67, v13, v67
	v_cvt_pk_bf16_f32 v64, v64, v65
	v_cvt_pk_bf16_f32 v65, v66, v67
	global_store_dwordx2 v72, v[64:65], s[28:29] offset:1024
	v_mul_f32_e32 v68, v68, v77
	v_mul_f32_e32 v68, v14, v68
	v_mul_f32_e32 v69, v69, v77
	v_mul_f32_e32 v69, v15, v69
	v_mul_f32_e32 v70, v70, v77
	v_mul_f32_e32 v70, v16, v70
	v_mul_f32_e32 v71, v71, v77
	v_mul_f32_e32 v71, v17, v71
	v_cvt_pk_bf16_f32 v68, v68, v69
	v_cvt_pk_bf16_f32 v69, v70, v71
	global_store_dwordx2 v72, v[68:69], s[28:29] offset:1536
	s_add_u32 s28, s28, 0x400000
	s_addc_u32 s29, s29, 0
	s_add_i32 s31, s31, 1
	s_cmp_lt_u32 s31, 30
	s_cbranch_scc1 .Lh_loop
; __device__ __forceinline__ u32x2 pack4(f32x4 a) { u32x2 w; w.x = cvt_pk_bf16(a[0], a[1]); w.y = cvt_pk_bf16(a[2], a[3]); return w; }
; __device__ __forceinline__ void p0_prologue(const Params& p, LAS unsigned char* lds, const int wave_s) {
;     ...
;     for (int row = blockIdx.x * 8 + wid; row < MTOK; row += G * 8) {
;         const float* xr = (row < NPROMPT ? p.in[I_XP] + (size_t)row * DM : p.in[I_XS] + (size_t)(row - NPROMPT) * DM) + lane * 4;
;         f32x4 v[4]; float ss = 0.f;
; #pragma unroll
;         for (int i = 0; i < 4; ++i) { v[i] = *(const f32x4*)(xr + 256 * i); ss += (v[i][0] * v[i][0] + v[i][1] * v[i][1]) + (v[i][2] * v[i][2] + v[i][3] * v[i][3]); }
; #pragma unroll
;         for (int o = 1; o < 64; o <<= 1) ss += __shfl_xor(ss, o);
;         const float rstd = rsqrtf(ss * (1.0f / 1024.0f) + EPSV);
;         bf16_t* hr = H + (size_t)row * DM + lane * 4;
; #pragma unroll
;         for (int i = 0; i < 4; ++i) *(u32x2*)(hr + 256 * i) = pack4(v[i] * rstd * g1[i]);
;     }
	s_add_u32 s26, s26, 0x800000
	s_addc_u32 s27, s27, 0
	s_add_i32 s30, s30, 1
	s_cmp_eq_u32 s30, 32
	s_cselect_b32 s26, s34, s26
	s_cselect_b32 s27, s35, s27
	global_load_dwordx4 v[56:59], v26, s[26:27]
	global_load_dwordx4 v[60:63], v26, s[26:27] offset:1024
	global_load_dwordx4 v[64:67], v26, s[26:27] offset:2048
	global_load_dwordx4 v[68:71], v26, s[26:27] offset:3072
	s_waitcnt vmcnt(8)
	v_mul_f32_e32 v74, v38, v38
	v_fmac_f32_e32 v74, v39, v39
	v_mul_f32_e32 v75, v40, v40
	v_fmac_f32_e32 v75, v41, v41
	v_add_f32_e32 v74, v74, v75
	v_mov_b32_e32 v73, v74
	v_mul_f32_e32 v74, v44, v44
	v_fmac_f32_e32 v74, v45, v45
	v_mul_f32_e32 v75, v46, v46
	v_fmac_f32_e32 v75, v47, v47
	v_add_f32_e32 v74, v74, v75
	v_add_f32_e32 v73, v73, v74
	v_mul_f32_e32 v74, v48, v48
	v_fmac_f32_e32 v74, v49, v49
	v_mul_f32_e32 v75, v50, v50
	v_fmac_f32_e32 v75, v51, v51
	v_add_f32_e32 v74, v74, v75
	v_add_f32_e32 v73, v73, v74
	v_mul_f32_e32 v74, v52, v52
	v_fmac_f32_e32 v74, v53, v53
	v_mul_f32_e32 v75, v54, v54
	v_fmac_f32_e32 v75, v55, v55
	v_add_f32_e32 v74, v74, v75
	v_add_f32_e32 v73, v73, v74
	ds_bpermute_b32 v74, v1, v73
	s_waitcnt lgkmcnt(0)
	v_add_f32_e32 v73, v73, v74
	ds_bpermute_b32 v74, v32, v73
	s_waitcnt lgkmcnt(0)
	v_add_f32_e32 v73, v73, v74
	ds_bpermute_b32 v74, v33, v73
	s_waitcnt lgkmcnt(0)
	v_add_f32_e32 v73, v73, v74
	ds_bpermute_b32 v74, v34, v73
	s_waitcnt lgkmcnt(0)
	v_add_f32_e32 v73, v73, v74
	ds_bpermute_b32 v74, v35, v73
	s_waitcnt lgkmcnt(0)
	v_add_f32_e32 v73, v73, v74
	ds_bpermute_b32 v74, v36, v73
	s_waitcnt lgkmcnt(0)
	v_add_f32_e32 v73, v73, v74
	v_fmamk_f32 v73, v73, 0x3a800000, v37
	v_mul_f32_e32 v74, 0x4b800000, v73
	v_cmp_gt_f32_e32 vcc, s13, v73
	s_nop 1
	v_cndmask_b32_e32 v73, v73, v74, vcc
	v_rsq_f32_e32 v73, v73
	s_nop 0
	v_mul_f32_e32 v74, 0x45800000, v73
	v_cndmask_b32_e32 v77, v73, v74, vcc
	v_mul_f32_e32 v38, v38, v77
	v_mul_f32_e32 v38, v2, v38
	v_mul_f32_e32 v39, v39, v77
	v_mul_f32_e32 v39, v3, v39
	v_mul_f32_e32 v40, v40, v77
	v_mul_f32_e32 v40, v4, v40
	v_mul_f32_e32 v41, v41, v77
	v_mul_f32_e32 v41, v5, v41
	v_cvt_pk_bf16_f32 v38, v38, v39
	v_cvt_pk_bf16_f32 v39, v40, v41
	global_store_dwordx2 v72, v[38:39], s[28:29]
	v_mul_f32_e32 v44, v44, v77
	v_mul_f32_e32 v44, v6, v44
	v_mul_f32_e32 v45, v45, v77
	v_mul_f32_e32 v45, v7, v45
	v_mul_f32_e32 v46, v46, v77
	v_mul_f32_e32 v46, v8, v46
	v_mul_f32_e32 v47, v47, v77
	v_mul_f32_e32 v47, v9, v47
	v_cvt_pk_bf16_f32 v44, v44, v45
	v_cvt_pk_bf16_f32 v45, v46, v47
	global_store_dwordx2 v72, v[44:45], s[28:29] offset:512
	v_mul_f32_e32 v48, v48, v77
	v_mul_f32_e32 v48, v10, v48
	v_mul_f32_e32 v49, v49, v77
	v_mul_f32_e32 v49, v11, v49
	v_mul_f32_e32 v50, v50, v77
	v_mul_f32_e32 v50, v12, v50
	v_mul_f32_e32 v51, v51, v77
	v_mul_f32_e32 v51, v13, v51
	v_cvt_pk_bf16_f32 v48, v48, v49
	v_cvt_pk_bf16_f32 v49, v50, v51
	global_store_dwordx2 v72, v[48:49], s[28:29] offset:1024
	v_mul_f32_e32 v52, v52, v77
	v_mul_f32_e32 v52, v14, v52
	v_mul_f32_e32 v53, v53, v77
	v_mul_f32_e32 v53, v15, v53
	v_mul_f32_e32 v54, v54, v77
	v_mul_f32_e32 v54, v16, v54
	v_mul_f32_e32 v55, v55, v77
	v_mul_f32_e32 v55, v17, v55
	v_cvt_pk_bf16_f32 v52, v52, v53
	v_cvt_pk_bf16_f32 v53, v54, v55
	global_store_dwordx2 v72, v[52:53], s[28:29] offset:1536
	s_add_u32 s28, s28, 0x400000
	s_addc_u32 s29, s29, 0
	s_waitcnt vmcnt(4)
	v_mul_f32_e32 v74, v56, v56
	v_fmac_f32_e32 v74, v57, v57
	v_mul_f32_e32 v75, v58, v58
	v_fmac_f32_e32 v75, v59, v59
	v_add_f32_e32 v74, v74, v75
	v_mov_b32_e32 v73, v74
	v_mul_f32_e32 v74, v60, v60
	v_fmac_f32_e32 v74, v61, v61
	v_mul_f32_e32 v75, v62, v62
	v_fmac_f32_e32 v75, v63, v63
	v_add_f32_e32 v74, v74, v75
	v_add_f32_e32 v73, v73, v74
	v_mul_f32_e32 v74, v64, v64
	v_fmac_f32_e32 v74, v65, v65
	v_mul_f32_e32 v75, v66, v66
	v_fmac_f32_e32 v75, v67, v67
	v_add_f32_e32 v74, v74, v75
	v_add_f32_e32 v73, v73, v74
	v_mul_f32_e32 v74, v68, v68
	v_fmac_f32_e32 v74, v69, v69
	v_mul_f32_e32 v75, v70, v70
	v_fmac_f32_e32 v75, v71, v71
	v_add_f32_e32 v74, v74, v75
	v_add_f32_e32 v73, v73, v74
	ds_bpermute_b32 v74, v1, v73
	s_waitcnt lgkmcnt(0)
	v_add_f32_e32 v73, v73, v74
	ds_bpermute_b32 v74, v32, v73
	s_waitcnt lgkmcnt(0)
	v_add_f32_e32 v73, v73, v74
	ds_bpermute_b32 v74, v33, v73
	s_waitcnt lgkmcnt(0)
	v_add_f32_e32 v73, v73, v74
	ds_bpermute_b32 v74, v34, v73
	s_waitcnt lgkmcnt(0)
	v_add_f32_e32 v73, v73, v74
	ds_bpermute_b32 v74, v35, v73
	s_waitcnt lgkmcnt(0)
	v_add_f32_e32 v73, v73, v74
	ds_bpermute_b32 v74, v36, v73
	s_waitcnt lgkmcnt(0)
	v_add_f32_e32 v73, v73, v74
	v_fmamk_f32 v73, v73, 0x3a800000, v37
	v_mul_f32_e32 v74, 0x4b800000, v73
	v_cmp_gt_f32_e32 vcc, s13, v73
	s_nop 1
	v_cndmask_b32_e32 v73, v73, v74, vcc
	v_rsq_f32_e32 v73, v73
	s_nop 0
	v_mul_f32_e32 v74, 0x45800000, v73
	v_cndmask_b32_e32 v77, v73, v74, vcc
	v_mul_f32_e32 v56, v56, v77
	v_mul_f32_e32 v56, v2, v56
	v_mul_f32_e32 v57, v57, v77
	v_mul_f32_e32 v57, v3, v57
	v_mul_f32_e32 v58, v58, v77
	v_mul_f32_e32 v58, v4, v58
	v_mul_f32_e32 v59, v59, v77
	v_mul_f32_e32 v59, v5, v59
	v_cvt_pk_bf16_f32 v56, v56, v57
	v_cvt_pk_bf16_f32 v57, v58, v59
	global_store_dwordx2 v72, v[56:57], s[28:29]
	v_mul_f32_e32 v60, v60, v77
	v_mul_f32_e32 v60, v6, v60
	v_mul_f32_e32 v61, v61, v77
	v_mul_f32_e32 v61, v7, v61
	v_mul_f32_e32 v62, v62, v77
	v_mul_f32_e32 v62, v8, v62
	v_mul_f32_e32 v63, v63, v77
	v_mul_f32_e32 v63, v9, v63
	v_cvt_pk_bf16_f32 v60, v60, v61
	v_cvt_pk_bf16_f32 v61, v62, v63
	global_store_dwordx2 v72, v[60:61], s[28:29] offset:512
	v_mul_f32_e32 v64, v64, v77
	v_mul_f32_e32 v64, v10, v64
	v_mul_f32_e32 v65, v65, v77
	v_mul_f32_e32 v65, v11, v65
	v_mul_f32_e32 v66, v66, v77
	v_mul_f32_e32 v66, v12, v66
	v_mul_f32_e32 v67, v67, v77
	v_mul_f32_e32 v67, v13, v67
	v_cvt_pk_bf16_f32 v64, v64, v65
	v_cvt_pk_bf16_f32 v65, v66, v67
	global_store_dwordx2 v72, v[64:65], s[28:29] offset:1024
	v_mul_f32_e32 v68, v68, v77
	v_mul_f32_e32 v68, v14, v68
	v_mul_f32_e32 v69, v69, v77
	v_mul_f32_e32 v69, v15, v69
	v_mul_f32_e32 v70, v70, v77
	v_mul_f32_e32 v70, v16, v70
	v_mul_f32_e32 v71, v71, v77
	v_mul_f32_e32 v71, v17, v71
	v_cvt_pk_bf16_f32 v68, v68, v69
	v_cvt_pk_bf16_f32 v69, v70, v71
	global_store_dwordx2 v72, v[68:69], s[28:29] offset:1536
	s_add_u32 s28, s28, 0x400000
	s_addc_u32 s29, s29, 0
	s_branch .LBB0_203
